# Attention: fast paths for fully-in-range dilation-16 tiles (static residue mask only) and shared tiles 9,10 (all keys valid), skipping per-element window compares
# speedup vs baseline: 1.1030x; 1.0028x over previous
.LBB0_156:
	s_waitcnt vmcnt(15)
	ds_write_b128 v154, v[84:87] offset:4096
	s_waitcnt vmcnt(13)
	ds_write_b128 v154, v[88:91] offset:5120
	s_waitcnt vmcnt(11)
	ds_write_b128 v154, v[96:99] offset:6144
	s_waitcnt vmcnt(9)
	ds_write_b128 v154, v[104:107] offset:7168
	ds_read_b128 v[48:51], v156 offset:4096
	ds_read_b128 v[164:167], v157 offset:4096
	ds_read_b128 v[168:171], v158 offset:4096
	ds_read_b128 v[172:175], v159 offset:4096
	ds_write_b128 v155, v[80:83]
	ds_write_b128 v155, v[92:95] offset:1024
	ds_write_b128 v155, v[100:103] offset:2048
	s_waitcnt vmcnt(8)
	ds_write_b128 v155, v[108:111] offset:3072
	s_setprio 1
	s_waitcnt lgkmcnt(7)
	v_mfma_f32_32x32x16_bf16 v[48:63], v[48:51], v[64:67], 0
	s_waitcnt lgkmcnt(6)
	v_mfma_f32_32x32x16_bf16 v[48:63], v[164:167], v[68:71], v[48:63]
	s_waitcnt lgkmcnt(5)
	v_mfma_f32_32x32x16_bf16 v[48:63], v[168:171], v[72:75], v[48:63]
	s_waitcnt lgkmcnt(4)
	v_mfma_f32_32x32x16_bf16 v[48:63], v[172:175], v[76:79], v[48:63]
	s_setprio 0
	v_mul_lo_u32 v14, s38, v151
	v_add3_u32 v14, s59, v144, v14
	v_cvt_f32_i32_e32 v167, v14
	v_cvt_f32_ubyte0_e32 v169, s38
	s_mov_b64 s[38:39], -1
	s_and_b64 vcc, exec, s[36:37]
	s_cbranch_vccz .LBB0_158
	v_mov_b32_e32 v14, v167
	s_mov_b64 s[38:39], 0
	s_cmp_gt_i32 s59, 0
	s_cbranch_scc1 .Lattn_slow_a
	s_cmp_gt_u32 s74, 10
	s_cbranch_scc1 .Lattn_fastA_a
	s_cmp_gt_u32 s74, 8
	s_cbranch_scc1 .Lattn_fastB_a
.Lattn_slow_a:
	v_sub_f32_e32 v15, v14, v179
	v_cmp_le_f32_e64 s[4:5], |v15|, v179
	v_sub_f32_e32 v15, v14, v161
	v_cmp_le_f32_e64 s[6:7], |v15|, v161
	s_and_b64 s[6:7], s[40:41], s[6:7]
	v_mul_f32_e32 v14, v141, v14
	s_and_b64 s[36:37], s[4:5], s[6:7]
	v_fmac_f32_e32 v14, 0x3e38aa3b, v48
	v_cndmask_b32_e64 v15, 0, 1.0, s[36:37]
	v_add_f32_e32 v14, v14, v15
	v_sub_f32_e32 v15, v167, v169
	s_or_b64 vcc, s[4:5], s[6:7]
	v_sub_f32_e32 v163, v15, v179
	v_cmp_le_f32_e64 s[4:5], |v163|, v179
	v_sub_f32_e32 v163, v15, v161
	v_cmp_le_f32_e64 s[6:7], |v163|, v161
	s_and_b64 s[6:7], s[42:43], s[6:7]
	v_mul_f32_e32 v15, v141, v15
	s_and_b64 s[36:37], s[4:5], s[6:7]
	v_fmac_f32_e32 v15, 0x3e38aa3b, v49
	v_cndmask_b32_e64 v163, 0, 1.0, s[36:37]
	v_add_f32_e32 v15, v15, v163
	v_fma_f32 v163, -2.0, v169, v167
	v_cndmask_b32_e32 v14, v246, v14, vcc
	v_sub_f32_e32 v164, v163, v179
	s_or_b64 vcc, s[4:5], s[6:7]
	v_cmp_le_f32_e64 s[4:5], |v164|, v179
	v_sub_f32_e32 v164, v163, v161
	v_cmp_le_f32_e64 s[6:7], |v164|, v161
	s_and_b64 s[6:7], s[44:45], s[6:7]
	v_mul_f32_e32 v163, v141, v163
	s_and_b64 s[36:37], s[4:5], s[6:7]
	v_fmac_f32_e32 v163, 0x3e38aa3b, v50
	v_cndmask_b32_e64 v164, 0, 1.0, s[36:37]
	v_add_f32_e32 v163, v163, v164
	v_fmamk_f32 v164, v169, 0xc0400000, v167
	v_cndmask_b32_e32 v15, v246, v15, vcc
	v_sub_f32_e32 v166, v164, v179
	s_or_b64 vcc, s[4:5], s[6:7]
	v_cmp_le_f32_e64 s[4:5], |v166|, v179
	v_sub_f32_e32 v166, v164, v161
	v_cmp_le_f32_e64 s[6:7], |v166|, v161
	s_and_b64 s[6:7], s[46:47], s[6:7]
	v_mul_f32_e32 v164, v141, v164
	s_and_b64 s[36:37], s[4:5], s[6:7]
	v_fmac_f32_e32 v164, 0x3e38aa3b, v51
	v_cndmask_b32_e64 v166, 0, 1.0, s[36:37]
	v_cndmask_b32_e32 v163, v246, v163, vcc
	v_add_f32_e32 v164, v164, v166
	s_or_b64 vcc, s[4:5], s[6:7]
	v_cndmask_b32_e32 v164, v246, v164, vcc
	v_max3_f32 v165, v14, s63, v15
	s_nop 0
	v_max3_f32 v168, v165, v163, v164
	v_fmamk_f32 v165, v169, 0xc1000000, v167
	s_nop 0
	v_sub_f32_e32 v166, v165, v179
	v_cmp_le_f32_e64 s[4:5], |v166|, v179
	v_sub_f32_e32 v166, v165, v161
	v_cmp_le_f32_e64 s[6:7], |v166|, v161
	s_and_b64 s[6:7], s[40:41], s[6:7]
	v_mul_f32_e32 v165, v141, v165
	s_and_b64 s[36:37], s[4:5], s[6:7]
	v_fmac_f32_e32 v165, 0x3e38aa3b, v52
	v_cndmask_b32_e64 v166, 0, 1.0, s[36:37]
	v_add_f32_e32 v165, v165, v166
	v_fmamk_f32 v166, v169, 0xc1100000, v167
	s_or_b64 vcc, s[4:5], s[6:7]
	v_sub_f32_e32 v170, v166, v179
	v_cmp_le_f32_e64 s[4:5], |v170|, v179
	v_sub_f32_e32 v170, v166, v161
	v_cmp_le_f32_e64 s[6:7], |v170|, v161
	s_and_b64 s[6:7], s[42:43], s[6:7]
	v_mul_f32_e32 v166, v141, v166
	s_and_b64 s[36:37], s[4:5], s[6:7]
	v_fmac_f32_e32 v166, 0x3e38aa3b, v53
	v_cndmask_b32_e64 v170, 0, 1.0, s[36:37]
	v_cndmask_b32_e32 v165, v246, v165, vcc
	v_add_f32_e32 v166, v166, v170
	s_or_b64 vcc, s[4:5], s[6:7]
	v_cndmask_b32_e32 v166, v246, v166, vcc
	s_nop 0
	v_max3_f32 v171, v168, v165, v166
	v_fmamk_f32 v168, v169, 0xc1200000, v167
	s_nop 0
	v_sub_f32_e32 v170, v168, v179
	v_cmp_le_f32_e64 s[4:5], |v170|, v179
	v_sub_f32_e32 v170, v168, v161
	v_cmp_le_f32_e64 s[6:7], |v170|, v161
	s_and_b64 s[6:7], s[44:45], s[6:7]
	v_mul_f32_e32 v168, v141, v168
	s_and_b64 s[36:37], s[4:5], s[6:7]
	v_fmac_f32_e32 v168, 0x3e38aa3b, v54
	v_cndmask_b32_e64 v170, 0, 1.0, s[36:37]
	v_add_f32_e32 v168, v168, v170
	v_fmamk_f32 v170, v169, 0xc1300000, v167
	s_or_b64 vcc, s[4:5], s[6:7]
	v_sub_f32_e32 v172, v170, v179
	v_cmp_le_f32_e64 s[4:5], |v172|, v179
	v_sub_f32_e32 v172, v170, v161
	v_cmp_le_f32_e64 s[6:7], |v172|, v161
	s_and_b64 s[6:7], s[46:47], s[6:7]
	v_mul_f32_e32 v170, v141, v170
	s_and_b64 s[36:37], s[4:5], s[6:7]
	v_fmac_f32_e32 v170, 0x3e38aa3b, v55
	v_cndmask_b32_e64 v172, 0, 1.0, s[36:37]
	v_cndmask_b32_e32 v168, v246, v168, vcc
	v_add_f32_e32 v170, v170, v172
	s_or_b64 vcc, s[4:5], s[6:7]
	v_cndmask_b32_e32 v170, v246, v170, vcc
	s_nop 0
	v_max3_f32 v173, v171, v168, v170
	v_fmamk_f32 v171, v169, 0xc1800000, v167
	s_nop 0
	v_sub_f32_e32 v172, v171, v179
	v_cmp_le_f32_e64 s[4:5], |v172|, v179
	v_sub_f32_e32 v172, v171, v161
	v_cmp_le_f32_e64 s[6:7], |v172|, v161
	s_and_b64 s[6:7], s[40:41], s[6:7]
	v_mul_f32_e32 v171, v141, v171
	s_and_b64 s[36:37], s[4:5], s[6:7]
	v_fmac_f32_e32 v171, 0x3e38aa3b, v56
	v_cndmask_b32_e64 v172, 0, 1.0, s[36:37]
	v_add_f32_e32 v171, v171, v172
	v_fmamk_f32 v172, v169, 0xc1880000, v167
	s_or_b64 vcc, s[4:5], s[6:7]
	v_sub_f32_e32 v174, v172, v179
	v_cmp_le_f32_e64 s[4:5], |v174|, v179
	v_sub_f32_e32 v174, v172, v161
	v_cmp_le_f32_e64 s[6:7], |v174|, v161
	s_and_b64 s[6:7], s[42:43], s[6:7]
	v_mul_f32_e32 v172, v141, v172
	s_and_b64 s[36:37], s[4:5], s[6:7]
	v_fmac_f32_e32 v172, 0x3e38aa3b, v57
	v_cndmask_b32_e64 v174, 0, 1.0, s[36:37]
	v_cndmask_b32_e32 v171, v246, v171, vcc
	v_add_f32_e32 v172, v172, v174
	s_or_b64 vcc, s[4:5], s[6:7]
	v_cndmask_b32_e32 v172, v246, v172, vcc
	s_nop 0
	v_max3_f32 v175, v173, v171, v172
	v_fmamk_f32 v173, v169, 0xc1900000, v167
	s_nop 0
	v_sub_f32_e32 v174, v173, v179
	v_cmp_le_f32_e64 s[4:5], |v174|, v179
	v_sub_f32_e32 v174, v173, v161
	v_cmp_le_f32_e64 s[6:7], |v174|, v161
	s_and_b64 s[6:7], s[44:45], s[6:7]
	v_mul_f32_e32 v173, v141, v173
	s_and_b64 s[36:37], s[4:5], s[6:7]
	v_fmac_f32_e32 v173, 0x3e38aa3b, v58
	v_cndmask_b32_e64 v174, 0, 1.0, s[36:37]
	v_add_f32_e32 v173, v173, v174
	v_fmamk_f32 v174, v169, 0xc1980000, v167
	s_or_b64 vcc, s[4:5], s[6:7]
	v_sub_f32_e32 v176, v174, v179
	v_cmp_le_f32_e64 s[4:5], |v176|, v179
	v_sub_f32_e32 v176, v174, v161
	v_cmp_le_f32_e64 s[6:7], |v176|, v161
	s_and_b64 s[6:7], s[46:47], s[6:7]
	v_mul_f32_e32 v174, v141, v174
	s_and_b64 s[36:37], s[4:5], s[6:7]
	v_fmac_f32_e32 v174, 0x3e38aa3b, v59
	v_cndmask_b32_e64 v176, 0, 1.0, s[36:37]
	v_cndmask_b32_e32 v173, v246, v173, vcc
	v_add_f32_e32 v174, v174, v176
	s_or_b64 vcc, s[4:5], s[6:7]
	v_cndmask_b32_e32 v174, v246, v174, vcc
	s_nop 0
	v_max3_f32 v177, v175, v173, v174
	v_fmamk_f32 v175, v169, 0xc1c00000, v167
	s_nop 0
	v_sub_f32_e32 v176, v175, v179
	v_cmp_le_f32_e64 s[4:5], |v176|, v179
	v_sub_f32_e32 v176, v175, v161
	v_cmp_le_f32_e64 s[6:7], |v176|, v161
	s_and_b64 s[6:7], s[40:41], s[6:7]
	v_mul_f32_e32 v175, v141, v175
	s_and_b64 s[36:37], s[4:5], s[6:7]
	v_fmac_f32_e32 v175, 0x3e38aa3b, v60
	v_cndmask_b32_e64 v176, 0, 1.0, s[36:37]
	v_add_f32_e32 v175, v175, v176
	v_fmamk_f32 v176, v169, 0xc1c80000, v167
	s_or_b64 vcc, s[4:5], s[6:7]
	v_sub_f32_e32 v178, v176, v179
	v_cmp_le_f32_e64 s[4:5], |v178|, v179
	v_sub_f32_e32 v178, v176, v161
	v_cmp_le_f32_e64 s[6:7], |v178|, v161
	s_and_b64 s[6:7], s[42:43], s[6:7]
	v_mul_f32_e32 v176, v141, v176
	s_and_b64 s[36:37], s[4:5], s[6:7]
	v_fmac_f32_e32 v176, 0x3e38aa3b, v61
	v_cndmask_b32_e64 v178, 0, 1.0, s[36:37]
	v_cndmask_b32_e32 v175, v246, v175, vcc
	v_add_f32_e32 v176, v176, v178
	s_or_b64 vcc, s[4:5], s[6:7]
	v_cndmask_b32_e32 v176, v246, v176, vcc
	s_nop 0
	v_max3_f32 v180, v177, v175, v176
	v_fmamk_f32 v177, v169, 0xc1d00000, v167
	s_nop 0
	v_sub_f32_e32 v178, v177, v179
	v_cmp_le_f32_e64 s[4:5], |v178|, v179
	v_sub_f32_e32 v178, v177, v161
	v_cmp_le_f32_e64 s[6:7], |v178|, v161
	s_and_b64 s[6:7], s[44:45], s[6:7]
	v_mul_f32_e32 v177, v141, v177
	s_and_b64 s[36:37], s[4:5], s[6:7]
	v_fmac_f32_e32 v177, 0x3e38aa3b, v62
	v_cndmask_b32_e64 v178, 0, 1.0, s[36:37]
	v_add_f32_e32 v177, v177, v178
	v_fmamk_f32 v178, v169, 0xc1d80000, v167
	s_or_b64 vcc, s[4:5], s[6:7]
	v_sub_f32_e32 v181, v178, v179
	v_cmp_le_f32_e64 s[4:5], |v181|, v179
	v_sub_f32_e32 v179, v178, v161
	v_cmp_le_f32_e64 s[6:7], |v179|, v161
	s_and_b64 s[6:7], s[46:47], s[6:7]
	v_mul_f32_e32 v178, v141, v178
	s_and_b64 s[36:37], s[4:5], s[6:7]
	v_fmac_f32_e32 v178, 0x3e38aa3b, v63
	v_cndmask_b32_e64 v179, 0, 1.0, s[36:37]
	v_cndmask_b32_e32 v177, v246, v177, vcc
	v_add_f32_e32 v178, v178, v179
	s_or_b64 vcc, s[4:5], s[6:7]
	v_cndmask_b32_e32 v178, v246, v178, vcc
	s_nop 0
	v_max3_f32 v180, v180, v177, v178
	s_branch .LBB0_158
.Lattn_fastA_a:
	s_nop 3
	v_mul_f32_e32 v14, v141, v167
	v_fmac_f32_e32 v14, 0x3e38aa3b, v48
	v_cndmask_b32_e64 v14, v246, v14, s[40:41]
	v_fmamk_f32 v15, v169, 0xbf800000, v167
	v_mul_f32_e32 v15, v141, v15
	v_fmac_f32_e32 v15, 0x3e38aa3b, v49
	v_cndmask_b32_e64 v15, v246, v15, s[42:43]
	v_fmamk_f32 v163, v169, 0xc0000000, v167
	v_mul_f32_e32 v163, v141, v163
	v_fmac_f32_e32 v163, 0x3e38aa3b, v50
	v_cndmask_b32_e64 v163, v246, v163, s[44:45]
	v_fmamk_f32 v164, v169, 0xc0400000, v167
	v_mul_f32_e32 v164, v141, v164
	v_fmac_f32_e32 v164, 0x3e38aa3b, v51
	v_cndmask_b32_e64 v164, v246, v164, s[46:47]
	v_fmamk_f32 v165, v169, 0xc1000000, v167
	v_mul_f32_e32 v165, v141, v165
	v_fmac_f32_e32 v165, 0x3e38aa3b, v52
	v_cndmask_b32_e64 v165, v246, v165, s[40:41]
	v_fmamk_f32 v166, v169, 0xc1100000, v167
	v_mul_f32_e32 v166, v141, v166
	v_fmac_f32_e32 v166, 0x3e38aa3b, v53
	v_cndmask_b32_e64 v166, v246, v166, s[42:43]
	v_fmamk_f32 v168, v169, 0xc1200000, v167
	v_mul_f32_e32 v168, v141, v168
	v_fmac_f32_e32 v168, 0x3e38aa3b, v54
	v_cndmask_b32_e64 v168, v246, v168, s[44:45]
	v_fmamk_f32 v170, v169, 0xc1300000, v167
	v_mul_f32_e32 v170, v141, v170
	v_fmac_f32_e32 v170, 0x3e38aa3b, v55
	v_cndmask_b32_e64 v170, v246, v170, s[46:47]
	v_fmamk_f32 v171, v169, 0xc1800000, v167
	v_mul_f32_e32 v171, v141, v171
	v_fmac_f32_e32 v171, 0x3e38aa3b, v56
	v_cndmask_b32_e64 v171, v246, v171, s[40:41]
	v_fmamk_f32 v172, v169, 0xc1880000, v167
	v_mul_f32_e32 v172, v141, v172
	v_fmac_f32_e32 v172, 0x3e38aa3b, v57
	v_cndmask_b32_e64 v172, v246, v172, s[42:43]
	v_fmamk_f32 v173, v169, 0xc1900000, v167
	v_mul_f32_e32 v173, v141, v173
	v_fmac_f32_e32 v173, 0x3e38aa3b, v58
	v_cndmask_b32_e64 v173, v246, v173, s[44:45]
	v_fmamk_f32 v174, v169, 0xc1980000, v167
	v_mul_f32_e32 v174, v141, v174
	v_fmac_f32_e32 v174, 0x3e38aa3b, v59
	v_cndmask_b32_e64 v174, v246, v174, s[46:47]
	v_fmamk_f32 v175, v169, 0xc1c00000, v167
	v_mul_f32_e32 v175, v141, v175
	v_fmac_f32_e32 v175, 0x3e38aa3b, v60
	v_cndmask_b32_e64 v175, v246, v175, s[40:41]
	v_fmamk_f32 v176, v169, 0xc1c80000, v167
	v_mul_f32_e32 v176, v141, v176
	v_fmac_f32_e32 v176, 0x3e38aa3b, v61
	v_cndmask_b32_e64 v176, v246, v176, s[42:43]
	v_fmamk_f32 v177, v169, 0xc1d00000, v167
	v_mul_f32_e32 v177, v141, v177
	v_fmac_f32_e32 v177, 0x3e38aa3b, v62
	v_cndmask_b32_e64 v177, v246, v177, s[44:45]
	v_fmamk_f32 v178, v169, 0xc1d80000, v167
	v_mul_f32_e32 v178, v141, v178
	v_fmac_f32_e32 v178, 0x3e38aa3b, v63
	v_cndmask_b32_e64 v178, v246, v178, s[46:47]
	v_max3_f32 v180, v14, s63, v15
	v_max3_f32 v180, v180, v163, v164
	v_max3_f32 v180, v180, v165, v166
	v_max3_f32 v180, v180, v168, v170
	v_max3_f32 v180, v180, v171, v172
	v_max3_f32 v180, v180, v173, v174
	v_max3_f32 v180, v180, v175, v176
	v_max3_f32 v180, v180, v177, v178
	s_branch .LBB0_158
.Lattn_fastB_a:
	s_nop 3
	v_cndmask_b32_e64 v180, 0, 1.0, s[40:41]
	v_mul_f32_e32 v14, v141, v167
	v_fmac_f32_e32 v14, 0x3e38aa3b, v48
	v_add_f32_e32 v14, v14, v180
	v_fmamk_f32 v165, v169, 0xc1000000, v167
	v_mul_f32_e32 v165, v141, v165
	v_fmac_f32_e32 v165, 0x3e38aa3b, v52
	v_add_f32_e32 v165, v165, v180
	v_fmamk_f32 v171, v169, 0xc1800000, v167
	v_mul_f32_e32 v171, v141, v171
	v_fmac_f32_e32 v171, 0x3e38aa3b, v56
	v_add_f32_e32 v171, v171, v180
	v_fmamk_f32 v175, v169, 0xc1c00000, v167
	v_mul_f32_e32 v175, v141, v175
	v_fmac_f32_e32 v175, 0x3e38aa3b, v60
	v_add_f32_e32 v175, v175, v180
	v_cndmask_b32_e64 v180, 0, 1.0, s[42:43]
	v_fmamk_f32 v15, v169, 0xbf800000, v167
	v_mul_f32_e32 v15, v141, v15
	v_fmac_f32_e32 v15, 0x3e38aa3b, v49
	v_add_f32_e32 v15, v15, v180
	v_fmamk_f32 v166, v169, 0xc1100000, v167
	v_mul_f32_e32 v166, v141, v166
	v_fmac_f32_e32 v166, 0x3e38aa3b, v53
	v_add_f32_e32 v166, v166, v180
	v_fmamk_f32 v172, v169, 0xc1880000, v167
	v_mul_f32_e32 v172, v141, v172
	v_fmac_f32_e32 v172, 0x3e38aa3b, v57
	v_add_f32_e32 v172, v172, v180
	v_fmamk_f32 v176, v169, 0xc1c80000, v167
	v_mul_f32_e32 v176, v141, v176
	v_fmac_f32_e32 v176, 0x3e38aa3b, v61
	v_add_f32_e32 v176, v176, v180
	v_cndmask_b32_e64 v180, 0, 1.0, s[44:45]
	v_fmamk_f32 v163, v169, 0xc0000000, v167
	v_mul_f32_e32 v163, v141, v163
	v_fmac_f32_e32 v163, 0x3e38aa3b, v50
	v_add_f32_e32 v163, v163, v180
	v_fmamk_f32 v168, v169, 0xc1200000, v167
	v_mul_f32_e32 v168, v141, v168
	v_fmac_f32_e32 v168, 0x3e38aa3b, v54
	v_add_f32_e32 v168, v168, v180
	v_fmamk_f32 v173, v169, 0xc1900000, v167
	v_mul_f32_e32 v173, v141, v173
	v_fmac_f32_e32 v173, 0x3e38aa3b, v58
	v_add_f32_e32 v173, v173, v180
	v_fmamk_f32 v177, v169, 0xc1d00000, v167
	v_mul_f32_e32 v177, v141, v177
	v_fmac_f32_e32 v177, 0x3e38aa3b, v62
	v_add_f32_e32 v177, v177, v180
	v_cndmask_b32_e64 v180, 0, 1.0, s[46:47]
	v_fmamk_f32 v164, v169, 0xc0400000, v167
	v_mul_f32_e32 v164, v141, v164
	v_fmac_f32_e32 v164, 0x3e38aa3b, v51
	v_add_f32_e32 v164, v164, v180
	v_fmamk_f32 v170, v169, 0xc1300000, v167
	v_mul_f32_e32 v170, v141, v170
	v_fmac_f32_e32 v170, 0x3e38aa3b, v55
	v_add_f32_e32 v170, v170, v180
	v_fmamk_f32 v174, v169, 0xc1980000, v167
	v_mul_f32_e32 v174, v141, v174
	v_fmac_f32_e32 v174, 0x3e38aa3b, v59
	v_add_f32_e32 v174, v174, v180
	v_fmamk_f32 v178, v169, 0xc1d80000, v167
	v_mul_f32_e32 v178, v141, v178
	v_fmac_f32_e32 v178, 0x3e38aa3b, v63
	v_add_f32_e32 v178, v178, v180
	v_max3_f32 v180, v14, s63, v15
	v_max3_f32 v180, v180, v163, v164
	v_max3_f32 v180, v180, v165, v166
	v_max3_f32 v180, v180, v168, v170
	v_max3_f32 v180, v180, v171, v172
	v_max3_f32 v180, v180, v173, v174
	v_max3_f32 v180, v180, v175, v176
	v_max3_f32 v180, v180, v177, v178
	s_branch .LBB0_158

.LBB0_184:
	s_waitcnt vmcnt(15)
	ds_write_b128 v154, v[2:5] offset:4096
	s_waitcnt vmcnt(13)
	ds_write_b128 v154, v[112:115] offset:5120
	s_waitcnt vmcnt(11)
	ds_write_b128 v154, v[120:123] offset:6144
	s_waitcnt vmcnt(9)
	ds_write_b128 v154, v[128:131] offset:7168
	ds_read_b128 v[48:51], v156 offset:4096
	ds_read_b128 v[164:167], v157 offset:4096
	ds_read_b128 v[168:171], v158 offset:4096
	ds_read_b128 v[172:175], v159 offset:4096
	ds_write_b128 v155, v[6:9]
	ds_write_b128 v155, v[10:13] offset:1024
	ds_write_b128 v155, v[116:119] offset:2048
	s_waitcnt vmcnt(8)
	ds_write_b128 v155, v[124:127] offset:3072
	s_setprio 1
	s_waitcnt lgkmcnt(7)
	v_mfma_f32_32x32x16_bf16 v[48:63], v[48:51], v[64:67], 0
	s_waitcnt lgkmcnt(6)
	v_mfma_f32_32x32x16_bf16 v[48:63], v[164:167], v[68:71], v[48:63]
	s_waitcnt lgkmcnt(5)
	v_mfma_f32_32x32x16_bf16 v[48:63], v[168:171], v[72:75], v[48:63]
	s_waitcnt lgkmcnt(4)
	v_mfma_f32_32x32x16_bf16 v[48:63], v[172:175], v[76:79], v[48:63]
	s_setprio 0
	v_mul_lo_u32 v0, s52, v151
	v_add3_u32 v0, s73, v144, v0
	v_cvt_f32_i32_e32 v166, v0
	v_cvt_f32_ubyte0_e32 v168, s52
	s_mov_b64 s[52:53], -1
	s_and_b64 vcc, exec, s[38:39]
	s_cbranch_vccz .LBB0_186
	v_mov_b32_e32 v0, v166
	s_mov_b64 s[52:53], 0
	s_cmp_gt_i32 s73, 0
	s_cbranch_scc1 .Lattn_slow_b
	s_cmp_gt_u32 s71, 10
	s_cbranch_scc1 .Lattn_fastA_b
	s_cmp_gt_u32 s71, 8
	s_cbranch_scc1 .Lattn_fastB_b
.Lattn_slow_b:
	v_sub_f32_e32 v14, v0, v178
	v_cmp_le_f32_e64 s[4:5], |v14|, v178
	v_sub_f32_e32 v14, v0, v161
	v_cmp_le_f32_e64 s[6:7], |v14|, v161
	s_and_b64 s[6:7], s[40:41], s[6:7]
	v_mul_f32_e32 v0, v141, v0
	s_and_b64 s[38:39], s[4:5], s[6:7]
	v_fmac_f32_e32 v0, 0x3e38aa3b, v48
	v_cndmask_b32_e64 v14, 0, 1.0, s[38:39]
	v_add_f32_e32 v0, v0, v14
	v_sub_f32_e32 v14, v166, v168
	s_or_b64 vcc, s[4:5], s[6:7]
	v_sub_f32_e32 v15, v14, v178
	v_cmp_le_f32_e64 s[4:5], |v15|, v178
	v_sub_f32_e32 v15, v14, v161
	v_cmp_le_f32_e64 s[6:7], |v15|, v161
	s_and_b64 s[6:7], s[42:43], s[6:7]
	v_mul_f32_e32 v14, v141, v14
	s_and_b64 s[38:39], s[4:5], s[6:7]
	v_fmac_f32_e32 v14, 0x3e38aa3b, v49
	v_cndmask_b32_e64 v15, 0, 1.0, s[38:39]
	v_add_f32_e32 v14, v14, v15
	v_fma_f32 v15, -2.0, v168, v166
	v_cndmask_b32_e32 v0, v246, v0, vcc
	v_sub_f32_e32 v163, v15, v178
	s_or_b64 vcc, s[4:5], s[6:7]
	v_cmp_le_f32_e64 s[4:5], |v163|, v178
	v_sub_f32_e32 v163, v15, v161
	v_cmp_le_f32_e64 s[6:7], |v163|, v161
	s_and_b64 s[6:7], s[44:45], s[6:7]
	v_mul_f32_e32 v15, v141, v15
	s_and_b64 s[38:39], s[4:5], s[6:7]
	v_fmac_f32_e32 v15, 0x3e38aa3b, v50
	v_cndmask_b32_e64 v163, 0, 1.0, s[38:39]
	v_add_f32_e32 v15, v15, v163
	v_fmamk_f32 v163, v168, 0xc0400000, v166
	v_cndmask_b32_e32 v14, v246, v14, vcc
	v_sub_f32_e32 v165, v163, v178
	s_or_b64 vcc, s[4:5], s[6:7]
	v_cmp_le_f32_e64 s[4:5], |v165|, v178
	v_sub_f32_e32 v165, v163, v161
	v_cmp_le_f32_e64 s[6:7], |v165|, v161
	s_and_b64 s[6:7], s[46:47], s[6:7]
	v_mul_f32_e32 v163, v141, v163
	s_and_b64 s[38:39], s[4:5], s[6:7]
	v_fmac_f32_e32 v163, 0x3e38aa3b, v51
	v_cndmask_b32_e64 v165, 0, 1.0, s[38:39]
	v_cndmask_b32_e32 v15, v246, v15, vcc
	v_add_f32_e32 v163, v163, v165
	s_or_b64 vcc, s[4:5], s[6:7]
	v_cndmask_b32_e32 v163, v246, v163, vcc
	v_max3_f32 v164, v0, s63, v14
	s_nop 0
	v_max3_f32 v167, v164, v15, v163
	v_fmamk_f32 v164, v168, 0xc1000000, v166
	s_nop 0
	v_sub_f32_e32 v165, v164, v178
	v_cmp_le_f32_e64 s[4:5], |v165|, v178
	v_sub_f32_e32 v165, v164, v161
	v_cmp_le_f32_e64 s[6:7], |v165|, v161
	s_and_b64 s[6:7], s[40:41], s[6:7]
	v_mul_f32_e32 v164, v141, v164
	s_and_b64 s[38:39], s[4:5], s[6:7]
	v_fmac_f32_e32 v164, 0x3e38aa3b, v52
	v_cndmask_b32_e64 v165, 0, 1.0, s[38:39]
	v_add_f32_e32 v164, v164, v165
	v_fmamk_f32 v165, v168, 0xc1100000, v166
	s_or_b64 vcc, s[4:5], s[6:7]
	v_sub_f32_e32 v169, v165, v178
	v_cmp_le_f32_e64 s[4:5], |v169|, v178
	v_sub_f32_e32 v169, v165, v161
	v_cmp_le_f32_e64 s[6:7], |v169|, v161
	s_and_b64 s[6:7], s[42:43], s[6:7]
	v_mul_f32_e32 v165, v141, v165
	s_and_b64 s[38:39], s[4:5], s[6:7]
	v_fmac_f32_e32 v165, 0x3e38aa3b, v53
	v_cndmask_b32_e64 v169, 0, 1.0, s[38:39]
	v_cndmask_b32_e32 v164, v246, v164, vcc
	v_add_f32_e32 v165, v165, v169
	s_or_b64 vcc, s[4:5], s[6:7]
	v_cndmask_b32_e32 v165, v246, v165, vcc
	s_nop 0
	v_max3_f32 v170, v167, v164, v165
	v_fmamk_f32 v167, v168, 0xc1200000, v166
	s_nop 0
	v_sub_f32_e32 v169, v167, v178
	v_cmp_le_f32_e64 s[4:5], |v169|, v178
	v_sub_f32_e32 v169, v167, v161
	v_cmp_le_f32_e64 s[6:7], |v169|, v161
	s_and_b64 s[6:7], s[44:45], s[6:7]
	v_mul_f32_e32 v167, v141, v167
	s_and_b64 s[38:39], s[4:5], s[6:7]
	v_fmac_f32_e32 v167, 0x3e38aa3b, v54
	v_cndmask_b32_e64 v169, 0, 1.0, s[38:39]
	v_add_f32_e32 v167, v167, v169
	v_fmamk_f32 v169, v168, 0xc1300000, v166
	s_or_b64 vcc, s[4:5], s[6:7]
	v_sub_f32_e32 v171, v169, v178
	v_cmp_le_f32_e64 s[4:5], |v171|, v178
	v_sub_f32_e32 v171, v169, v161
	v_cmp_le_f32_e64 s[6:7], |v171|, v161
	s_and_b64 s[6:7], s[46:47], s[6:7]
	v_mul_f32_e32 v169, v141, v169
	s_and_b64 s[38:39], s[4:5], s[6:7]
	v_fmac_f32_e32 v169, 0x3e38aa3b, v55
	v_cndmask_b32_e64 v171, 0, 1.0, s[38:39]
	v_cndmask_b32_e32 v167, v246, v167, vcc
	v_add_f32_e32 v169, v169, v171
	s_or_b64 vcc, s[4:5], s[6:7]
	v_cndmask_b32_e32 v169, v246, v169, vcc
	s_nop 0
	v_max3_f32 v172, v170, v167, v169
	v_fmamk_f32 v170, v168, 0xc1800000, v166
	s_nop 0
	v_sub_f32_e32 v171, v170, v178
	v_cmp_le_f32_e64 s[4:5], |v171|, v178
	v_sub_f32_e32 v171, v170, v161
	v_cmp_le_f32_e64 s[6:7], |v171|, v161
	s_and_b64 s[6:7], s[40:41], s[6:7]
	v_mul_f32_e32 v170, v141, v170
	s_and_b64 s[38:39], s[4:5], s[6:7]
	v_fmac_f32_e32 v170, 0x3e38aa3b, v56
	v_cndmask_b32_e64 v171, 0, 1.0, s[38:39]
	v_add_f32_e32 v170, v170, v171
	v_fmamk_f32 v171, v168, 0xc1880000, v166
	s_or_b64 vcc, s[4:5], s[6:7]
	v_sub_f32_e32 v173, v171, v178
	v_cmp_le_f32_e64 s[4:5], |v173|, v178
	v_sub_f32_e32 v173, v171, v161
	v_cmp_le_f32_e64 s[6:7], |v173|, v161
	s_and_b64 s[6:7], s[42:43], s[6:7]
	v_mul_f32_e32 v171, v141, v171
	s_and_b64 s[38:39], s[4:5], s[6:7]
	v_fmac_f32_e32 v171, 0x3e38aa3b, v57
	v_cndmask_b32_e64 v173, 0, 1.0, s[38:39]
	v_cndmask_b32_e32 v170, v246, v170, vcc
	v_add_f32_e32 v171, v171, v173
	s_or_b64 vcc, s[4:5], s[6:7]
	v_cndmask_b32_e32 v171, v246, v171, vcc
	s_nop 0
	v_max3_f32 v174, v172, v170, v171
	v_fmamk_f32 v172, v168, 0xc1900000, v166
	s_nop 0
	v_sub_f32_e32 v173, v172, v178
	v_cmp_le_f32_e64 s[4:5], |v173|, v178
	v_sub_f32_e32 v173, v172, v161
	v_cmp_le_f32_e64 s[6:7], |v173|, v161
	s_and_b64 s[6:7], s[44:45], s[6:7]
	v_mul_f32_e32 v172, v141, v172
	s_and_b64 s[38:39], s[4:5], s[6:7]
	v_fmac_f32_e32 v172, 0x3e38aa3b, v58
	v_cndmask_b32_e64 v173, 0, 1.0, s[38:39]
	v_add_f32_e32 v172, v172, v173
	v_fmamk_f32 v173, v168, 0xc1980000, v166
	s_or_b64 vcc, s[4:5], s[6:7]
	v_sub_f32_e32 v175, v173, v178
	v_cmp_le_f32_e64 s[4:5], |v175|, v178
	v_sub_f32_e32 v175, v173, v161
	v_cmp_le_f32_e64 s[6:7], |v175|, v161
	s_and_b64 s[6:7], s[46:47], s[6:7]
	v_mul_f32_e32 v173, v141, v173
	s_and_b64 s[38:39], s[4:5], s[6:7]
	v_fmac_f32_e32 v173, 0x3e38aa3b, v59
	v_cndmask_b32_e64 v175, 0, 1.0, s[38:39]
	v_cndmask_b32_e32 v172, v246, v172, vcc
	v_add_f32_e32 v173, v173, v175
	s_or_b64 vcc, s[4:5], s[6:7]
	v_cndmask_b32_e32 v173, v246, v173, vcc
	s_nop 0
	v_max3_f32 v176, v174, v172, v173
	v_fmamk_f32 v174, v168, 0xc1c00000, v166
	s_nop 0
	v_sub_f32_e32 v175, v174, v178
	v_cmp_le_f32_e64 s[4:5], |v175|, v178
	v_sub_f32_e32 v175, v174, v161
	v_cmp_le_f32_e64 s[6:7], |v175|, v161
	s_and_b64 s[6:7], s[40:41], s[6:7]
	v_mul_f32_e32 v174, v141, v174
	s_and_b64 s[38:39], s[4:5], s[6:7]
	v_fmac_f32_e32 v174, 0x3e38aa3b, v60
	v_cndmask_b32_e64 v175, 0, 1.0, s[38:39]
	v_add_f32_e32 v174, v174, v175
	v_fmamk_f32 v175, v168, 0xc1c80000, v166
	s_or_b64 vcc, s[4:5], s[6:7]
	v_sub_f32_e32 v177, v175, v178
	v_cmp_le_f32_e64 s[4:5], |v177|, v178
	v_sub_f32_e32 v177, v175, v161
	v_cmp_le_f32_e64 s[6:7], |v177|, v161
	s_and_b64 s[6:7], s[42:43], s[6:7]
	v_mul_f32_e32 v175, v141, v175
	s_and_b64 s[38:39], s[4:5], s[6:7]
	v_fmac_f32_e32 v175, 0x3e38aa3b, v61
	v_cndmask_b32_e64 v177, 0, 1.0, s[38:39]
	v_cndmask_b32_e32 v174, v246, v174, vcc
	v_add_f32_e32 v175, v175, v177
	s_or_b64 vcc, s[4:5], s[6:7]
	v_cndmask_b32_e32 v175, v246, v175, vcc
	s_nop 0
	v_max3_f32 v179, v176, v174, v175
	v_fmamk_f32 v176, v168, 0xc1d00000, v166
	s_nop 0
	v_sub_f32_e32 v177, v176, v178
	v_cmp_le_f32_e64 s[4:5], |v177|, v178
	v_sub_f32_e32 v177, v176, v161
	v_cmp_le_f32_e64 s[6:7], |v177|, v161
	s_and_b64 s[6:7], s[44:45], s[6:7]
	v_mul_f32_e32 v176, v141, v176
	s_and_b64 s[38:39], s[4:5], s[6:7]
	v_fmac_f32_e32 v176, 0x3e38aa3b, v62
	v_cndmask_b32_e64 v177, 0, 1.0, s[38:39]
	v_add_f32_e32 v176, v176, v177
	v_fmamk_f32 v177, v168, 0xc1d80000, v166
	s_or_b64 vcc, s[4:5], s[6:7]
	v_sub_f32_e32 v180, v177, v178
	v_cmp_le_f32_e64 s[4:5], |v180|, v178
	v_sub_f32_e32 v178, v177, v161
	v_cmp_le_f32_e64 s[6:7], |v178|, v161
	s_and_b64 s[6:7], s[46:47], s[6:7]
	v_mul_f32_e32 v177, v141, v177
	s_and_b64 s[38:39], s[4:5], s[6:7]
	v_fmac_f32_e32 v177, 0x3e38aa3b, v63
	v_cndmask_b32_e64 v178, 0, 1.0, s[38:39]
	v_cndmask_b32_e32 v176, v246, v176, vcc
	v_add_f32_e32 v177, v177, v178
	s_or_b64 vcc, s[4:5], s[6:7]
	v_cndmask_b32_e32 v177, v246, v177, vcc
	s_nop 0
	v_max3_f32 v179, v179, v176, v177
	s_branch .LBB0_186
.Lattn_fastA_b:
	s_nop 3
	v_mul_f32_e32 v0, v141, v166
	v_fmac_f32_e32 v0, 0x3e38aa3b, v48
	v_cndmask_b32_e64 v0, v246, v0, s[40:41]
	v_fmamk_f32 v14, v168, 0xbf800000, v166
	v_mul_f32_e32 v14, v141, v14
	v_fmac_f32_e32 v14, 0x3e38aa3b, v49
	v_cndmask_b32_e64 v14, v246, v14, s[42:43]
	v_fmamk_f32 v15, v168, 0xc0000000, v166
	v_mul_f32_e32 v15, v141, v15
	v_fmac_f32_e32 v15, 0x3e38aa3b, v50
	v_cndmask_b32_e64 v15, v246, v15, s[44:45]
	v_fmamk_f32 v163, v168, 0xc0400000, v166
	v_mul_f32_e32 v163, v141, v163
	v_fmac_f32_e32 v163, 0x3e38aa3b, v51
	v_cndmask_b32_e64 v163, v246, v163, s[46:47]
	v_fmamk_f32 v164, v168, 0xc1000000, v166
	v_mul_f32_e32 v164, v141, v164
	v_fmac_f32_e32 v164, 0x3e38aa3b, v52
	v_cndmask_b32_e64 v164, v246, v164, s[40:41]
	v_fmamk_f32 v165, v168, 0xc1100000, v166
	v_mul_f32_e32 v165, v141, v165
	v_fmac_f32_e32 v165, 0x3e38aa3b, v53
	v_cndmask_b32_e64 v165, v246, v165, s[42:43]
	v_fmamk_f32 v167, v168, 0xc1200000, v166
	v_mul_f32_e32 v167, v141, v167
	v_fmac_f32_e32 v167, 0x3e38aa3b, v54
	v_cndmask_b32_e64 v167, v246, v167, s[44:45]
	v_fmamk_f32 v169, v168, 0xc1300000, v166
	v_mul_f32_e32 v169, v141, v169
	v_fmac_f32_e32 v169, 0x3e38aa3b, v55
	v_cndmask_b32_e64 v169, v246, v169, s[46:47]
	v_fmamk_f32 v170, v168, 0xc1800000, v166
	v_mul_f32_e32 v170, v141, v170
	v_fmac_f32_e32 v170, 0x3e38aa3b, v56
	v_cndmask_b32_e64 v170, v246, v170, s[40:41]
	v_fmamk_f32 v171, v168, 0xc1880000, v166
	v_mul_f32_e32 v171, v141, v171
	v_fmac_f32_e32 v171, 0x3e38aa3b, v57
	v_cndmask_b32_e64 v171, v246, v171, s[42:43]
	v_fmamk_f32 v172, v168, 0xc1900000, v166
	v_mul_f32_e32 v172, v141, v172
	v_fmac_f32_e32 v172, 0x3e38aa3b, v58
	v_cndmask_b32_e64 v172, v246, v172, s[44:45]
	v_fmamk_f32 v173, v168, 0xc1980000, v166
	v_mul_f32_e32 v173, v141, v173
	v_fmac_f32_e32 v173, 0x3e38aa3b, v59
	v_cndmask_b32_e64 v173, v246, v173, s[46:47]
	v_fmamk_f32 v174, v168, 0xc1c00000, v166
	v_mul_f32_e32 v174, v141, v174
	v_fmac_f32_e32 v174, 0x3e38aa3b, v60
	v_cndmask_b32_e64 v174, v246, v174, s[40:41]
	v_fmamk_f32 v175, v168, 0xc1c80000, v166
	v_mul_f32_e32 v175, v141, v175
	v_fmac_f32_e32 v175, 0x3e38aa3b, v61
	v_cndmask_b32_e64 v175, v246, v175, s[42:43]
	v_fmamk_f32 v176, v168, 0xc1d00000, v166
	v_mul_f32_e32 v176, v141, v176
	v_fmac_f32_e32 v176, 0x3e38aa3b, v62
	v_cndmask_b32_e64 v176, v246, v176, s[44:45]
	v_fmamk_f32 v177, v168, 0xc1d80000, v166
	v_mul_f32_e32 v177, v141, v177
	v_fmac_f32_e32 v177, 0x3e38aa3b, v63
	v_cndmask_b32_e64 v177, v246, v177, s[46:47]
	v_max3_f32 v179, v0, s63, v14
	v_max3_f32 v179, v179, v15, v163
	v_max3_f32 v179, v179, v164, v165
	v_max3_f32 v179, v179, v167, v169
	v_max3_f32 v179, v179, v170, v171
	v_max3_f32 v179, v179, v172, v173
	v_max3_f32 v179, v179, v174, v175
	v_max3_f32 v179, v179, v176, v177
	s_branch .LBB0_186
.Lattn_fastB_b:
	s_nop 3
	v_cndmask_b32_e64 v179, 0, 1.0, s[40:41]
	v_mul_f32_e32 v0, v141, v166
	v_fmac_f32_e32 v0, 0x3e38aa3b, v48
	v_add_f32_e32 v0, v0, v179
	v_fmamk_f32 v164, v168, 0xc1000000, v166
	v_mul_f32_e32 v164, v141, v164
	v_fmac_f32_e32 v164, 0x3e38aa3b, v52
	v_add_f32_e32 v164, v164, v179
	v_fmamk_f32 v170, v168, 0xc1800000, v166
	v_mul_f32_e32 v170, v141, v170
	v_fmac_f32_e32 v170, 0x3e38aa3b, v56
	v_add_f32_e32 v170, v170, v179
	v_fmamk_f32 v174, v168, 0xc1c00000, v166
	v_mul_f32_e32 v174, v141, v174
	v_fmac_f32_e32 v174, 0x3e38aa3b, v60
	v_add_f32_e32 v174, v174, v179
	v_cndmask_b32_e64 v179, 0, 1.0, s[42:43]
	v_fmamk_f32 v14, v168, 0xbf800000, v166
	v_mul_f32_e32 v14, v141, v14
	v_fmac_f32_e32 v14, 0x3e38aa3b, v49
	v_add_f32_e32 v14, v14, v179
	v_fmamk_f32 v165, v168, 0xc1100000, v166
	v_mul_f32_e32 v165, v141, v165
	v_fmac_f32_e32 v165, 0x3e38aa3b, v53
	v_add_f32_e32 v165, v165, v179
	v_fmamk_f32 v171, v168, 0xc1880000, v166
	v_mul_f32_e32 v171, v141, v171
	v_fmac_f32_e32 v171, 0x3e38aa3b, v57
	v_add_f32_e32 v171, v171, v179
	v_fmamk_f32 v175, v168, 0xc1c80000, v166
	v_mul_f32_e32 v175, v141, v175
	v_fmac_f32_e32 v175, 0x3e38aa3b, v61
	v_add_f32_e32 v175, v175, v179
	v_cndmask_b32_e64 v179, 0, 1.0, s[44:45]
	v_fmamk_f32 v15, v168, 0xc0000000, v166
	v_mul_f32_e32 v15, v141, v15
	v_fmac_f32_e32 v15, 0x3e38aa3b, v50
	v_add_f32_e32 v15, v15, v179
	v_fmamk_f32 v167, v168, 0xc1200000, v166
	v_mul_f32_e32 v167, v141, v167
	v_fmac_f32_e32 v167, 0x3e38aa3b, v54
	v_add_f32_e32 v167, v167, v179
	v_fmamk_f32 v172, v168, 0xc1900000, v166
	v_mul_f32_e32 v172, v141, v172
	v_fmac_f32_e32 v172, 0x3e38aa3b, v58
	v_add_f32_e32 v172, v172, v179
	v_fmamk_f32 v176, v168, 0xc1d00000, v166
	v_mul_f32_e32 v176, v141, v176
	v_fmac_f32_e32 v176, 0x3e38aa3b, v62
	v_add_f32_e32 v176, v176, v179
	v_cndmask_b32_e64 v179, 0, 1.0, s[46:47]
	v_fmamk_f32 v163, v168, 0xc0400000, v166
	v_mul_f32_e32 v163, v141, v163
	v_fmac_f32_e32 v163, 0x3e38aa3b, v51
	v_add_f32_e32 v163, v163, v179
	v_fmamk_f32 v169, v168, 0xc1300000, v166
	v_mul_f32_e32 v169, v141, v169
	v_fmac_f32_e32 v169, 0x3e38aa3b, v55
	v_add_f32_e32 v169, v169, v179
	v_fmamk_f32 v173, v168, 0xc1980000, v166
	v_mul_f32_e32 v173, v141, v173
	v_fmac_f32_e32 v173, 0x3e38aa3b, v59
	v_add_f32_e32 v173, v173, v179
	v_fmamk_f32 v177, v168, 0xc1d80000, v166
	v_mul_f32_e32 v177, v141, v177
	v_fmac_f32_e32 v177, 0x3e38aa3b, v63
	v_add_f32_e32 v177, v177, v179
	v_max3_f32 v179, v0, s63, v14
	v_max3_f32 v179, v179, v15, v163
	v_max3_f32 v179, v179, v164, v165
	v_max3_f32 v179, v179, v167, v169
	v_max3_f32 v179, v179, v170, v171
	v_max3_f32 v179, v179, v172, v173
	v_max3_f32 v179, v179, v174, v175
	v_max3_f32 v179, v179, v176, v177
	s_branch .LBB0_186
